# hg_b phase B: all loads of a chunk issued up front
# baseline (speedup 1.0000x reference)
; __device__ __forceinline__ unsigned f2bf(float f) { unsigned u = __float_as_uint(f); return (u + 0x7fffu + ((u >> 16) & 1u)) >> 16; }
; #define MFMA16(a, b, c) __builtin_amdgcn_mfma_f32_16x16x32_bf16((a), (b), (c), 0, 0, 0)
; __device__ __forceinline__ void hg_b_item(const Params& p, LAS unsigned char* lds, int item, bool dry = false) {
;     ...
;         for (int g = 0; g < 16; ++g) { const int n = 16 * G16 + g; const size_t ro = (size_t)n * 64 * ZW;
;             const float dec = pD[n * 128];
;             bf16x8 aV[2], bK[2];
; #pragma unroll
;             for (int k = 0; k < 2; ++k) { aV[k] = *(const bf16x8*)(pV + ro + 32 * k); bK[k] = *(const bf16x8*)(pK + ro + 32 * k); }
; #pragma unroll
;             for (int r = 0; r < 4; ++r) SB[g * 2176 + (4 * fq + r) * 136 + dg] = (bf16_t)f2bf(S[r]);
;             S = S * dec;
; #pragma unroll
;             for (int k = 0; k < 2; ++k) S = MFMA16(aV[k], bK[k], S); }
.LBB0_204:
	v_lshl_add_u64 v[14:15], s[24:25], 0, v[10:11]
	s_nop 1
	v_bfe_u32 v18, v3, 16, 1
	v_bfe_u32 v19, v4, 16, 1
	v_add3_u32 v40, v3, v18, s27
	v_add_co_u32_e64 v18, s[4:5], s28, v14
	v_lshl_add_u64 v[12:13], s[24:25], 0, v[8:9]
	v_add3_u32 v41, v4, v19, s27
	v_addc_co_u32_e64 v19, s[4:5], 0, v15, s[4:5]
	v_add_co_u32_e64 v44, s[4:5], s29, v12
	v_bfe_u32 v0, v2, 16, 1
	s_nop 0
	v_addc_co_u32_e64 v45, s[4:5], 0, v13, s[4:5]
	v_add_co_u32_e64 v52, s[4:5], s30, v14
	v_lshl_add_u64 v[16:17], s[24:25], 0, v[6:7]
	s_nop 0
	v_addc_co_u32_e64 v53, s[4:5], 0, v15, s[4:5]
	v_add_co_u32_e64 v60, s[4:5], s31, v12
	v_add_u32_e32 v39, s16, v37
	s_nop 0
	v_addc_co_u32_e64 v61, s[4:5], 0, v13, s[4:5]
	v_add_co_u32_e64 v68, s[4:5], s33, v14
	v_bfe_u32 v20, v5, 16, 1
	s_nop 0
	v_addc_co_u32_e64 v69, s[4:5], 0, v15, s[4:5]
	v_add_co_u32_e64 v76, s[4:5], s34, v12
	v_add3_u32 v21, v2, v0, s27
	s_nop 0
	v_addc_co_u32_e64 v77, s[4:5], 0, v13, s[4:5]
	v_add_co_u32_e64 v84, s[4:5], s35, v14
	v_add_co_u32_e32 v32, vcc, 0x402000, v14
	s_nop 0
	v_addc_co_u32_e64 v85, s[4:5], 0, v15, s[4:5]
	v_add_co_u32_e64 v92, s[4:5], s36, v12
	v_add3_u32 v20, v5, v20, s27
	s_nop 0
	v_addc_co_u32_e64 v93, s[4:5], 0, v13, s[4:5]
	v_add_co_u32_e64 v104, s[4:5], s37, v14
	global_load_dword v0, v[16:17], off
	global_load_dword v154, v[16:17], off offset:512
	global_load_dword v156, v[16:17], off offset:1024
	global_load_dword v158, v[16:17], off offset:1536
	global_load_dword v160, v[16:17], off offset:2048
	global_load_dword v164, v[16:17], off offset:2560
	global_load_dword v166, v[16:17], off offset:3072
	global_load_dword v168, v[16:17], off offset:3584
	v_addc_co_u32_e64 v105, s[4:5], 0, v15, s[4:5]
	v_add_co_u32_e64 v124, s[4:5], s40, v12
	ds_write_b16_d16_hi v39, v21
	ds_write_b16_d16_hi v39, v40 offset:272
	ds_write_b16_d16_hi v39, v41 offset:544
	ds_write_b16_d16_hi v39, v20 offset:816
	v_addc_co_u32_e64 v125, s[4:5], 0, v13, s[4:5]
	v_add_co_u32_e64 v132, s[4:5], s41, v14
	v_addc_co_u32_e32 v33, vcc, 0, v15, vcc
	s_nop 0
	v_addc_co_u32_e64 v133, s[4:5], 0, v15, s[4:5]
	v_add_co_u32_e64 v140, s[4:5], s43, v12
	s_add_i32 s16, s16, 0x8800
	s_nop 0
	v_addc_co_u32_e64 v141, s[4:5], 0, v13, s[4:5]
	v_add_co_u32_e64 v150, s[4:5], s45, v14
	v_lshl_add_u64 v[10:11], v[10:11], 0, s[14:15]
	s_nop 0
	v_addc_co_u32_e64 v151, s[4:5], 0, v15, s[4:5]
	global_load_dwordx4 v[14:17], v[18:19], off
	s_nop 0
	global_load_dwordx4 v[18:21], v[18:19], off offset:64
	s_nop 0
	global_load_dwordx4 v[40:43], v[44:45], off offset:2048
	s_nop 0
	global_load_dwordx4 v[44:47], v[44:45], off offset:2112
	s_nop 0
	global_load_dwordx4 v[48:51], v[52:53], off
	s_nop 0
	global_load_dwordx4 v[52:55], v[52:53], off offset:64
	s_nop 0
	global_load_dwordx4 v[56:59], v[60:61], off offset:2048
	s_nop 0
	global_load_dwordx4 v[60:63], v[60:61], off offset:2112
	s_nop 0
	global_load_dwordx4 v[64:67], v[68:69], off
	s_nop 0
	global_load_dwordx4 v[68:71], v[68:69], off offset:64
	s_nop 0
	global_load_dwordx4 v[72:75], v[76:77], off offset:2048
	s_nop 0
	global_load_dwordx4 v[76:79], v[76:77], off offset:2112
	s_nop 0
	global_load_dwordx4 v[80:83], v[84:85], off
	s_nop 0
	global_load_dwordx4 v[84:87], v[84:85], off offset:64
	s_nop 0
	global_load_dwordx4 v[88:91], v[92:93], off offset:2048
	s_nop 0
	global_load_dwordx4 v[92:95], v[92:93], off offset:2112
	s_nop 0
	global_load_dwordx4 v[96:99], v[124:125], off offset:2048
	global_load_dwordx4 v[100:103], v[104:105], off
	s_nop 0
	global_load_dwordx4 v[104:107], v[104:105], off offset:64
	s_nop 0
	global_load_dwordx4 v[108:111], v[32:33], off
	v_add_co_u32_e64 v152, s[4:5], s46, v12
	v_add_co_u32_e32 v12, vcc, 0x401000, v12
	s_nop 0
	v_addc_co_u32_e64 v153, s[4:5], 0, v13, s[4:5]
	v_addc_co_u32_e32 v13, vcc, 0, v13, vcc
	global_load_dwordx4 v[112:115], v[32:33], off offset:64
	global_load_dwordx4 v[116:119], v[12:13], off offset:2048
	global_load_dwordx4 v[120:123], v[12:13], off offset:2112
	s_nop 0
	global_load_dwordx4 v[124:127], v[124:125], off offset:2112
	s_nop 0
	global_load_dwordx4 v[128:131], v[132:133], off
	s_nop 0
	global_load_dwordx4 v[132:135], v[132:133], off offset:64
	s_nop 0
	global_load_dwordx4 v[136:139], v[140:141], off offset:2048
	s_nop 0
	global_load_dwordx4 v[140:143], v[140:141], off offset:2112
	s_nop 0
	global_load_dwordx4 v[144:147], v[150:151], off
	v_lshl_add_u64 v[8:9], v[8:9], 0, s[14:15]
	v_lshl_add_u64 v[6:7], v[6:7], 0, s[18:19]
	s_cmp_eq_u32 s16, 0x11000
	s_waitcnt vmcnt(36)
	v_pk_mul_f32 v[4:5], v[4:5], v[0:1] op_sel_hi:[1,0]
	v_pk_mul_f32 v[2:3], v[2:3], v[0:1] op_sel_hi:[1,0]
	s_waitcnt vmcnt(7)
	s_nop 0
	v_mfma_f32_16x16x32_bf16 v[2:5], v[108:111], v[116:119], v[2:5]
	global_load_dwordx4 v[108:111], v[150:151], off offset:64
	global_load_dwordx4 v[116:119], v[152:153], off offset:2048
	s_nop 0
	global_load_dwordx4 v[150:153], v[152:153], off offset:2112
	s_waitcnt vmcnt(9)
; __device__ __forceinline__ unsigned f2bf(float f) { unsigned u = __float_as_uint(f); return (u + 0x7fffu + ((u >> 16) & 1u)) >> 16; }
; #define MFMA16(a, b, c) __builtin_amdgcn_mfma_f32_16x16x32_bf16((a), (b), (c), 0, 0, 0)
; __device__ __forceinline__ void hg_b_item(const Params& p, LAS unsigned char* lds, int item, bool dry = false) {
;     ...
;         for (int g = 0; g < 16; ++g) { const int n = 16 * G16 + g; const size_t ro = (size_t)n * 64 * ZW;
;             const float dec = pD[n * 128];
;             bf16x8 aV[2], bK[2];
; #pragma unroll
;             for (int k = 0; k < 2; ++k) { aV[k] = *(const bf16x8*)(pV + ro + 32 * k); bK[k] = *(const bf16x8*)(pK + ro + 32 * k); }
; #pragma unroll
;             for (int r = 0; r < 4; ++r) SB[g * 2176 + (4 * fq + r) * 136 + dg] = (bf16_t)f2bf(S[r]);
;             S = S * dec;
; #pragma unroll
;             for (int k = 0; k < 2; ++k) S = MFMA16(aV[k], bK[k], S); }
;         asm volatile("s_waitcnt lgkmcnt(0)" ::: "memory"); __builtin_amdgcn_s_barrier(); asm volatile("" ::: "memory");
	v_mfma_f32_16x16x32_bf16 v[2:5], v[112:115], v[120:123], v[2:5]
	s_nop 7
	v_bfe_u32 v0, v2, 16, 1
	v_bfe_u32 v12, v3, 16, 1
	v_bfe_u32 v13, v4, 16, 1
	v_bfe_u32 v32, v5, 16, 1
	v_pk_mul_f32 v[114:115], v[4:5], v[154:155] op_sel_hi:[1,0]
	v_pk_mul_f32 v[112:113], v[2:3], v[154:155] op_sel_hi:[1,0]
	v_add3_u32 v0, v2, v0, s27
	v_add3_u32 v12, v3, v12, s27
	v_add3_u32 v13, v4, v13, s27
	v_add3_u32 v32, v5, v32, s27
	v_mfma_f32_16x16x32_bf16 v[2:5], v[14:17], v[40:43], v[112:115]
	ds_write_b16_d16_hi v39, v0 offset:4352
	ds_write_b16_d16_hi v39, v12 offset:4624
	ds_write_b16_d16_hi v39, v13 offset:4896
	ds_write_b16_d16_hi v39, v32 offset:5168
	v_mfma_f32_16x16x32_bf16 v[2:5], v[18:21], v[44:47], v[2:5]
	s_nop 7
	v_bfe_u32 v0, v2, 16, 1
	v_bfe_u32 v16, v3, 16, 1
	v_bfe_u32 v17, v4, 16, 1
	v_bfe_u32 v18, v5, 16, 1
	v_pk_mul_f32 v[14:15], v[4:5], v[156:157] op_sel_hi:[1,0]
	v_pk_mul_f32 v[12:13], v[2:3], v[156:157] op_sel_hi:[1,0]
	v_add3_u32 v0, v2, v0, s27
	v_add3_u32 v16, v3, v16, s27
	v_add3_u32 v17, v4, v17, s27
	v_add3_u32 v18, v5, v18, s27
	v_mfma_f32_16x16x32_bf16 v[2:5], v[48:51], v[56:59], v[12:15]
	ds_write_b16_d16_hi v39, v0 offset:8704
	ds_write_b16_d16_hi v39, v16 offset:8976
	ds_write_b16_d16_hi v39, v17 offset:9248
	ds_write_b16_d16_hi v39, v18 offset:9520
	v_mfma_f32_16x16x32_bf16 v[2:5], v[52:55], v[60:63], v[2:5]
	s_nop 7
	v_bfe_u32 v0, v2, 16, 1
	v_bfe_u32 v16, v3, 16, 1
	v_bfe_u32 v17, v4, 16, 1
	v_bfe_u32 v18, v5, 16, 1
	v_pk_mul_f32 v[14:15], v[4:5], v[158:159] op_sel_hi:[1,0]
	v_pk_mul_f32 v[12:13], v[2:3], v[158:159] op_sel_hi:[1,0]
	v_add3_u32 v0, v2, v0, s27
	v_add3_u32 v16, v3, v16, s27
	v_add3_u32 v17, v4, v17, s27
	v_add3_u32 v18, v5, v18, s27
	v_mfma_f32_16x16x32_bf16 v[2:5], v[64:67], v[72:75], v[12:15]
	ds_write_b16_d16_hi v39, v0 offset:13056
	ds_write_b16_d16_hi v39, v16 offset:13328
	ds_write_b16_d16_hi v39, v17 offset:13600
	ds_write_b16_d16_hi v39, v18 offset:13872
	v_mfma_f32_16x16x32_bf16 v[2:5], v[68:71], v[76:79], v[2:5]
	s_nop 7
	v_bfe_u32 v0, v2, 16, 1
	v_bfe_u32 v16, v3, 16, 1
	v_bfe_u32 v17, v4, 16, 1
	v_bfe_u32 v18, v5, 16, 1
	v_pk_mul_f32 v[14:15], v[4:5], v[160:161] op_sel_hi:[1,0]
	v_pk_mul_f32 v[12:13], v[2:3], v[160:161] op_sel_hi:[1,0]
	v_add3_u32 v0, v2, v0, s27
	v_add3_u32 v16, v3, v16, s27
	v_add3_u32 v17, v4, v17, s27
	v_add3_u32 v18, v5, v18, s27
	v_mfma_f32_16x16x32_bf16 v[2:5], v[80:83], v[88:91], v[12:15]
	ds_write_b16_d16_hi v39, v0 offset:17408
	ds_write_b16_d16_hi v39, v16 offset:17680
	ds_write_b16_d16_hi v39, v17 offset:17952
	ds_write_b16_d16_hi v39, v18 offset:18224
	v_mfma_f32_16x16x32_bf16 v[2:5], v[84:87], v[92:95], v[2:5]
	s_nop 7
	v_bfe_u32 v0, v2, 16, 1
	v_bfe_u32 v16, v3, 16, 1
	v_bfe_u32 v17, v4, 16, 1
	v_bfe_u32 v18, v5, 16, 1
	v_pk_mul_f32 v[14:15], v[4:5], v[164:165] op_sel_hi:[1,0]
	v_pk_mul_f32 v[12:13], v[2:3], v[164:165] op_sel_hi:[1,0]
	v_add3_u32 v0, v2, v0, s27
	v_add3_u32 v16, v3, v16, s27
	v_add3_u32 v17, v4, v17, s27
	v_add3_u32 v18, v5, v18, s27
	v_mfma_f32_16x16x32_bf16 v[2:5], v[100:103], v[96:99], v[12:15]
	ds_write_b16_d16_hi v39, v0 offset:21760
	ds_write_b16_d16_hi v39, v16 offset:22032
	ds_write_b16_d16_hi v39, v17 offset:22304
	ds_write_b16_d16_hi v39, v18 offset:22576
	s_waitcnt vmcnt(8)
	v_mfma_f32_16x16x32_bf16 v[2:5], v[104:107], v[124:127], v[2:5]
	s_nop 7
	v_bfe_u32 v0, v2, 16, 1
	v_bfe_u32 v16, v3, 16, 1
	v_bfe_u32 v17, v4, 16, 1
	v_bfe_u32 v18, v5, 16, 1
	v_pk_mul_f32 v[14:15], v[4:5], v[166:167] op_sel_hi:[1,0]
	v_pk_mul_f32 v[12:13], v[2:3], v[166:167] op_sel_hi:[1,0]
	v_add3_u32 v0, v2, v0, s27
	v_add3_u32 v16, v3, v16, s27
	v_add3_u32 v17, v4, v17, s27
	v_add3_u32 v18, v5, v18, s27
	s_waitcnt vmcnt(5)
	v_mfma_f32_16x16x32_bf16 v[2:5], v[128:131], v[136:139], v[12:15]
	ds_write_b16_d16_hi v39, v0 offset:26112
	ds_write_b16_d16_hi v39, v16 offset:26384
	ds_write_b16_d16_hi v39, v17 offset:26656
	ds_write_b16_d16_hi v39, v18 offset:26928
	s_waitcnt vmcnt(4)
	v_mfma_f32_16x16x32_bf16 v[2:5], v[132:135], v[140:143], v[2:5]
	s_nop 7
	v_pk_mul_f32 v[14:15], v[4:5], v[168:169] op_sel_hi:[1,0]
	v_pk_mul_f32 v[12:13], v[2:3], v[168:169] op_sel_hi:[1,0]
	v_bfe_u32 v0, v2, 16, 1
	v_bfe_u32 v16, v3, 16, 1
	s_waitcnt vmcnt(1)
	v_mfma_f32_16x16x32_bf16 v[12:15], v[144:147], v[116:119], v[12:15]
	v_bfe_u32 v17, v4, 16, 1
	v_bfe_u32 v18, v5, 16, 1
	v_add3_u32 v0, v2, v0, s27
	v_add3_u32 v16, v3, v16, s27
	v_add3_u32 v17, v4, v17, s27
	v_add3_u32 v18, v5, v18, s27
	s_waitcnt vmcnt(0)
	v_mfma_f32_16x16x32_bf16 v[2:5], v[108:111], v[150:153], v[12:15]
	ds_write_b16_d16_hi v39, v0 offset:30464
	ds_write_b16_d16_hi v39, v16 offset:30736
	ds_write_b16_d16_hi v39, v17 offset:31008
	ds_write_b16_d16_hi v39, v18 offset:31280
	s_cbranch_scc0 .LBB0_204
	s_lshl_b32 s16, s8, 4
	s_add_i32 s16, s16, s51
	s_waitcnt lgkmcnt(0)
	s_barrier
; #define LAS __attribute__((address_space(3)))
; __device__ __forceinline__ unsigned f2bf(float f) { unsigned u = __float_as_uint(f); return (u + 0x7fffu + ((u >> 16) & 1u)) >> 16; }
; __device__ __forceinline__ float bf2f(unsigned h) { return __uint_as_float(h << 16); }
; #define MFMA16(a, b, c) __builtin_amdgcn_mfma_f32_16x16x32_bf16((a), (b), (c), 0, 0, 0)
; __device__ __forceinline__ void hg_b_item(const Params& p, LAS unsigned char* lds, int item, bool dry = false) {
;     ...
;         for (int c2 = 0; c2 < 2; ++c2) { const int g = wave + 8 * c2, nB = 16 * G16 + g; const size_t roB = (size_t)nB * 64 * ZW;
;             bf16x8 bS[4];
; #pragma unroll
;             for (int k = 0; k < 4; ++k) bS[k] = *(const LAS bf16x8*)(SB + g * 2176 + fr * 136 + 32 * k + 8 * fq);
; #pragma unroll
;             for (int lt = 0; lt < 4; ++lt) { f32x4 acc = (f32x4){0.f, 0.f, 0.f, 0.f}; unsigned short oO[4];
; #pragma unroll
;                 for (int r = 0; r < 4; ++r) oO[r] = pO[(size_t)(nB * 64 + 16 * lt + r) * D];
; #pragma unroll
;                 for (int k = 0; k < 4; ++k) { const bf16x8 a = *(const bf16x8*)(pQ + roB + (size_t)(16 * lt) * ZW + 32 * k); acc = MFMA16(a, bS[k], acc); }
; #pragma unroll
;                 for (int r = 0; r < 4; ++r) { const float nv = bf2f(oO[r]) + acc[r]; if (!dry) pO[(size_t)(nB * 64 + 16 * lt + r) * D] = (bf16_t)f2bf(nv); else if (nv == 123456.0f) pO[0] = 0; } } }
	s_add_i32 s8, s8, 1
	v_lshl_add_u64 v[28:29], v[28:29], 0, s[20:21]
	v_lshl_add_u64 v[22:23], v[22:23], 0, s[20:21]
	v_lshl_add_u64 v[30:31], v[30:31], 0, s[22:23]
	v_mad_i64_i32 v[32:33], s[54:55], s16, v36, v[24:25]
	s_lshl_b32 s4, s16, 6
	ds_read_b128 v[18:21], v38 offset:0
	ds_read_b128 v[14:17], v38 offset:64
	ds_read_b128 v[10:13], v38 offset:128
	ds_read_b128 v[6:9], v38 offset:192
	s_or_b32 s54, s4, 2
	s_ashr_i32 s55, s54, 31
	s_lshl_b64 s[54:55], s[54:55], 11
	v_lshl_add_u64 v[62:63], v[26:27], 0, s[54:55]
	s_or_b32 s54, s4, 18
	s_ashr_i32 s55, s54, 31
	s_lshl_b64 s[54:55], s[54:55], 11
	v_lshl_add_u64 v[64:65], v[26:27], 0, s[54:55]
	s_or_b32 s54, s4, 34
	s_ashr_i32 s55, s54, 31
	s_lshl_b64 s[54:55], s[54:55], 11
	v_lshl_add_u64 v[66:67], v[26:27], 0, s[54:55]
	s_or_b32 s54, s4, 50
	s_ashr_i32 s55, s54, 31
	s_lshl_b64 s[54:55], s[54:55], 11
	v_lshl_add_u64 v[68:69], v[26:27], 0, s[54:55]
	v_add_co_u32_e32 v56, vcc, s47, v32
	s_nop 1
	v_addc_co_u32_e32 v57, vcc, 0, v33, vcc
	v_add_co_u32_e32 v58, vcc, s48, v32
	s_nop 1
	v_addc_co_u32_e32 v59, vcc, 0, v33, vcc
	v_add_co_u32_e32 v60, vcc, s49, v32
	s_nop 1
	v_addc_co_u32_e32 v61, vcc, 0, v33, vcc
	global_load_dwordx4 v[80:83], v[32:33], off
	global_load_dwordx4 v[84:87], v[32:33], off offset:64
	global_load_dwordx4 v[88:91], v[32:33], off offset:128
	global_load_dwordx4 v[92:95], v[32:33], off offset:192
	global_load_ushort v39, v[62:63], off offset:-4096
	global_load_ushort v40, v[62:63], off offset:-2048
	global_load_ushort v41, v[62:63], off
	global_load_ushort v42, v[62:63], off offset:2048
	global_load_dwordx4 v[96:99], v[56:57], off
	global_load_dwordx4 v[100:103], v[56:57], off offset:64
	global_load_dwordx4 v[104:107], v[56:57], off offset:128
	global_load_dwordx4 v[108:111], v[56:57], off offset:192
	global_load_ushort v43, v[64:65], off offset:-4096
	global_load_ushort v44, v[64:65], off offset:-2048
	global_load_ushort v45, v[64:65], off
	global_load_ushort v46, v[64:65], off offset:2048
	global_load_dwordx4 v[112:115], v[58:59], off
	global_load_dwordx4 v[116:119], v[58:59], off offset:64
	global_load_dwordx4 v[120:123], v[58:59], off offset:128
	global_load_dwordx4 v[124:127], v[58:59], off offset:192
	global_load_ushort v47, v[66:67], off offset:-4096
	global_load_ushort v48, v[66:67], off offset:-2048
	global_load_ushort v49, v[66:67], off
	global_load_ushort v50, v[66:67], off offset:2048
	global_load_dwordx4 v[128:131], v[60:61], off
	global_load_dwordx4 v[132:135], v[60:61], off offset:64
	global_load_dwordx4 v[136:139], v[60:61], off offset:128
	global_load_dwordx4 v[140:143], v[60:61], off offset:192
	global_load_ushort v51, v[68:69], off offset:-4096
	global_load_ushort v52, v[68:69], off offset:-2048
	global_load_ushort v53, v[68:69], off
	global_load_ushort v54, v[68:69], off offset:2048
	s_waitcnt vmcnt(24) lgkmcnt(0)
	v_mfma_f32_16x16x32_bf16 v[72:75], v[80:83], v[18:21], 0
	v_mfma_f32_16x16x32_bf16 v[72:75], v[84:87], v[14:17], v[72:75]
	v_mfma_f32_16x16x32_bf16 v[72:75], v[88:91], v[10:13], v[72:75]
	v_mfma_f32_16x16x32_bf16 v[72:75], v[92:95], v[6:9], v[72:75]
	v_lshlrev_b32_e32 v39, 16, v39
	v_lshlrev_b32_e32 v40, 16, v40
	v_lshlrev_b32_e32 v41, 16, v41
	v_lshlrev_b32_e32 v42, 16, v42
	s_nop 7
	v_add_f32_e32 v76, v72, v39
	v_add_f32_e32 v77, v73, v40
	v_add_f32_e32 v78, v74, v41
	v_add_f32_e32 v79, v75, v42
	v_bfe_u32 v144, v76, 16, 1
	v_bfe_u32 v145, v77, 16, 1
	v_bfe_u32 v146, v78, 16, 1
	v_bfe_u32 v147, v79, 16, 1
	v_add3_u32 v76, v76, v144, s27
	v_add3_u32 v77, v77, v145, s27
	v_add3_u32 v78, v78, v146, s27
	v_add3_u32 v79, v79, v147, s27
	global_store_short_d16_hi v[62:63], v76, off offset:-4096
	global_store_short_d16_hi v[62:63], v77, off offset:-2048
	global_store_short_d16_hi v[62:63], v78, off
	global_store_short_d16_hi v[62:63], v79, off offset:2048
	s_waitcnt vmcnt(20)
	v_mfma_f32_16x16x32_bf16 v[72:75], v[96:99], v[18:21], 0
	v_mfma_f32_16x16x32_bf16 v[72:75], v[100:103], v[14:17], v[72:75]
	v_mfma_f32_16x16x32_bf16 v[72:75], v[104:107], v[10:13], v[72:75]
	v_mfma_f32_16x16x32_bf16 v[72:75], v[108:111], v[6:9], v[72:75]
	v_lshlrev_b32_e32 v43, 16, v43
	v_lshlrev_b32_e32 v44, 16, v44
	v_lshlrev_b32_e32 v45, 16, v45
	v_lshlrev_b32_e32 v46, 16, v46
	s_nop 7
	v_add_f32_e32 v76, v72, v43
	v_add_f32_e32 v77, v73, v44
	v_add_f32_e32 v78, v74, v45
	v_add_f32_e32 v79, v75, v46
	v_bfe_u32 v144, v76, 16, 1
	v_bfe_u32 v145, v77, 16, 1
	v_bfe_u32 v146, v78, 16, 1
	v_bfe_u32 v147, v79, 16, 1
	v_add3_u32 v76, v76, v144, s27
	v_add3_u32 v77, v77, v145, s27
	v_add3_u32 v78, v78, v146, s27
	v_add3_u32 v79, v79, v147, s27
	global_store_short_d16_hi v[64:65], v76, off offset:-4096
	global_store_short_d16_hi v[64:65], v77, off offset:-2048
	global_store_short_d16_hi v[64:65], v78, off
	global_store_short_d16_hi v[64:65], v79, off offset:2048
	s_waitcnt vmcnt(16)
	v_mfma_f32_16x16x32_bf16 v[72:75], v[112:115], v[18:21], 0
	v_mfma_f32_16x16x32_bf16 v[72:75], v[116:119], v[14:17], v[72:75]
	v_mfma_f32_16x16x32_bf16 v[72:75], v[120:123], v[10:13], v[72:75]
	v_mfma_f32_16x16x32_bf16 v[72:75], v[124:127], v[6:9], v[72:75]
	v_lshlrev_b32_e32 v47, 16, v47
	v_lshlrev_b32_e32 v48, 16, v48
	v_lshlrev_b32_e32 v49, 16, v49
	v_lshlrev_b32_e32 v50, 16, v50
	s_nop 7
	v_add_f32_e32 v76, v72, v47
	v_add_f32_e32 v77, v73, v48
	v_add_f32_e32 v78, v74, v49
	v_add_f32_e32 v79, v75, v50
	v_bfe_u32 v144, v76, 16, 1
	v_bfe_u32 v145, v77, 16, 1
	v_bfe_u32 v146, v78, 16, 1
	v_bfe_u32 v147, v79, 16, 1
	v_add3_u32 v76, v76, v144, s27
	v_add3_u32 v77, v77, v145, s27
	v_add3_u32 v78, v78, v146, s27
	v_add3_u32 v79, v79, v147, s27
	global_store_short_d16_hi v[66:67], v76, off offset:-4096
	global_store_short_d16_hi v[66:67], v77, off offset:-2048
	global_store_short_d16_hi v[66:67], v78, off
	global_store_short_d16_hi v[66:67], v79, off offset:2048
	s_waitcnt vmcnt(12)
; #define LAS __attribute__((address_space(3)))
; __device__ __forceinline__ unsigned f2bf(float f) { unsigned u = __float_as_uint(f); return (u + 0x7fffu + ((u >> 16) & 1u)) >> 16; }
; __device__ __forceinline__ float bf2f(unsigned h) { return __uint_as_float(h << 16); }
; #define MFMA16(a, b, c) __builtin_amdgcn_mfma_f32_16x16x32_bf16((a), (b), (c), 0, 0, 0)
; __device__ __forceinline__ void hg_b_item(const Params& p, LAS unsigned char* lds, int item, bool dry = false) {
;     ...
;         for (int c2 = 0; c2 < 2; ++c2) { const int g = wave + 8 * c2, nB = 16 * G16 + g; const size_t roB = (size_t)nB * 64 * ZW;
;             bf16x8 bS[4];
; #pragma unroll
;             for (int k = 0; k < 4; ++k) bS[k] = *(const LAS bf16x8*)(SB + g * 2176 + fr * 136 + 32 * k + 8 * fq);
; #pragma unroll
;             for (int lt = 0; lt < 4; ++lt) { f32x4 acc = (f32x4){0.f, 0.f, 0.f, 0.f}; unsigned short oO[4];
; #pragma unroll
;                 for (int r = 0; r < 4; ++r) oO[r] = pO[(size_t)(nB * 64 + 16 * lt + r) * D];
; #pragma unroll
;                 for (int k = 0; k < 4; ++k) { const bf16x8 a = *(const bf16x8*)(pQ + roB + (size_t)(16 * lt) * ZW + 32 * k); acc = MFMA16(a, bS[k], acc); }
; #pragma unroll
;                 for (int r = 0; r < 4; ++r) { const float nv = bf2f(oO[r]) + acc[r]; if (!dry) pO[(size_t)(nB * 64 + 16 * lt + r) * D] = (bf16_t)f2bf(nv); else if (nv == 123456.0f) pO[0] = 0; } } }
	v_mfma_f32_16x16x32_bf16 v[72:75], v[128:131], v[18:21], 0
	v_mfma_f32_16x16x32_bf16 v[72:75], v[132:135], v[14:17], v[72:75]
	v_mfma_f32_16x16x32_bf16 v[72:75], v[136:139], v[10:13], v[72:75]
	v_mfma_f32_16x16x32_bf16 v[72:75], v[140:143], v[6:9], v[72:75]
	v_lshlrev_b32_e32 v51, 16, v51
	v_lshlrev_b32_e32 v52, 16, v52
	v_lshlrev_b32_e32 v53, 16, v53
	v_lshlrev_b32_e32 v54, 16, v54
	s_nop 7
	v_add_f32_e32 v76, v72, v51
	v_add_f32_e32 v77, v73, v52
	v_add_f32_e32 v78, v74, v53
	v_add_f32_e32 v79, v75, v54
	v_bfe_u32 v144, v76, 16, 1
	v_bfe_u32 v145, v77, 16, 1
	v_bfe_u32 v146, v78, 16, 1
	v_bfe_u32 v147, v79, 16, 1
	v_add3_u32 v76, v76, v144, s27
	v_add3_u32 v77, v77, v145, s27
	v_add3_u32 v78, v78, v146, s27
	v_add3_u32 v79, v79, v147, s27
	global_store_short_d16_hi v[68:69], v76, off offset:-4096
	global_store_short_d16_hi v[68:69], v77, off offset:-2048
	global_store_short_d16_hi v[68:69], v78, off
	global_store_short_d16_hi v[68:69], v79, off offset:2048
	s_add_i32 s16, s16, 8
	v_mad_i64_i32 v[32:33], s[54:55], s16, v36, v[24:25]
	s_lshl_b32 s4, s16, 6
	ds_read_b128 v[18:21], v38 offset:34816
	ds_read_b128 v[14:17], v38 offset:34880
	ds_read_b128 v[10:13], v38 offset:34944
	ds_read_b128 v[6:9], v38 offset:35008
	s_or_b32 s54, s4, 2
	s_ashr_i32 s55, s54, 31
	s_lshl_b64 s[54:55], s[54:55], 11
	v_lshl_add_u64 v[62:63], v[26:27], 0, s[54:55]
	s_or_b32 s54, s4, 18
	s_ashr_i32 s55, s54, 31
	s_lshl_b64 s[54:55], s[54:55], 11
	v_lshl_add_u64 v[64:65], v[26:27], 0, s[54:55]
	s_or_b32 s54, s4, 34
	s_ashr_i32 s55, s54, 31
	s_lshl_b64 s[54:55], s[54:55], 11
	v_lshl_add_u64 v[66:67], v[26:27], 0, s[54:55]
	s_or_b32 s54, s4, 50
	s_ashr_i32 s55, s54, 31
	s_lshl_b64 s[54:55], s[54:55], 11
	v_lshl_add_u64 v[68:69], v[26:27], 0, s[54:55]
	v_add_co_u32_e32 v56, vcc, s47, v32
	s_nop 1
	v_addc_co_u32_e32 v57, vcc, 0, v33, vcc
	v_add_co_u32_e32 v58, vcc, s48, v32
	s_nop 1
	v_addc_co_u32_e32 v59, vcc, 0, v33, vcc
	v_add_co_u32_e32 v60, vcc, s49, v32
	s_nop 1
	v_addc_co_u32_e32 v61, vcc, 0, v33, vcc
	global_load_dwordx4 v[80:83], v[32:33], off
	global_load_dwordx4 v[84:87], v[32:33], off offset:64
	global_load_dwordx4 v[88:91], v[32:33], off offset:128
	global_load_dwordx4 v[92:95], v[32:33], off offset:192
	global_load_ushort v39, v[62:63], off offset:-4096
	global_load_ushort v40, v[62:63], off offset:-2048
	global_load_ushort v41, v[62:63], off
	global_load_ushort v42, v[62:63], off offset:2048
	global_load_dwordx4 v[96:99], v[56:57], off
	global_load_dwordx4 v[100:103], v[56:57], off offset:64
	global_load_dwordx4 v[104:107], v[56:57], off offset:128
	global_load_dwordx4 v[108:111], v[56:57], off offset:192
	global_load_ushort v43, v[64:65], off offset:-4096
	global_load_ushort v44, v[64:65], off offset:-2048
	global_load_ushort v45, v[64:65], off
	global_load_ushort v46, v[64:65], off offset:2048
	global_load_dwordx4 v[112:115], v[58:59], off
	global_load_dwordx4 v[116:119], v[58:59], off offset:64
	global_load_dwordx4 v[120:123], v[58:59], off offset:128
	global_load_dwordx4 v[124:127], v[58:59], off offset:192
	global_load_ushort v47, v[66:67], off offset:-4096
	global_load_ushort v48, v[66:67], off offset:-2048
	global_load_ushort v49, v[66:67], off
	global_load_ushort v50, v[66:67], off offset:2048
	global_load_dwordx4 v[128:131], v[60:61], off
	global_load_dwordx4 v[132:135], v[60:61], off offset:64
	global_load_dwordx4 v[136:139], v[60:61], off offset:128
	global_load_dwordx4 v[140:143], v[60:61], off offset:192
	global_load_ushort v51, v[68:69], off offset:-4096
	global_load_ushort v52, v[68:69], off offset:-2048
	global_load_ushort v53, v[68:69], off
	global_load_ushort v54, v[68:69], off offset:2048
	s_waitcnt vmcnt(24) lgkmcnt(0)
; #define LAS __attribute__((address_space(3)))
; __device__ __forceinline__ unsigned f2bf(float f) { unsigned u = __float_as_uint(f); return (u + 0x7fffu + ((u >> 16) & 1u)) >> 16; }
; __device__ __forceinline__ float bf2f(unsigned h) { return __uint_as_float(h << 16); }
; #define MFMA16(a, b, c) __builtin_amdgcn_mfma_f32_16x16x32_bf16((a), (b), (c), 0, 0, 0)
; __device__ __forceinline__ void hg_b_item(const Params& p, LAS unsigned char* lds, int item, bool dry = false) {
;     ...
;         for (int c2 = 0; c2 < 2; ++c2) { const int g = wave + 8 * c2, nB = 16 * G16 + g; const size_t roB = (size_t)nB * 64 * ZW;
;             bf16x8 bS[4];
; #pragma unroll
;             for (int k = 0; k < 4; ++k) bS[k] = *(const LAS bf16x8*)(SB + g * 2176 + fr * 136 + 32 * k + 8 * fq);
; #pragma unroll
;             for (int lt = 0; lt < 4; ++lt) { f32x4 acc = (f32x4){0.f, 0.f, 0.f, 0.f}; unsigned short oO[4];
; #pragma unroll
;                 for (int r = 0; r < 4; ++r) oO[r] = pO[(size_t)(nB * 64 + 16 * lt + r) * D];
; #pragma unroll
;                 for (int k = 0; k < 4; ++k) { const bf16x8 a = *(const bf16x8*)(pQ + roB + (size_t)(16 * lt) * ZW + 32 * k); acc = MFMA16(a, bS[k], acc); }
; #pragma unroll
;                 for (int r = 0; r < 4; ++r) { const float nv = bf2f(oO[r]) + acc[r]; if (!dry) pO[(size_t)(nB * 64 + 16 * lt + r) * D] = (bf16_t)f2bf(nv); else if (nv == 123456.0f) pO[0] = 0; } } }
	v_mfma_f32_16x16x32_bf16 v[72:75], v[80:83], v[18:21], 0
	v_mfma_f32_16x16x32_bf16 v[72:75], v[84:87], v[14:17], v[72:75]
	v_mfma_f32_16x16x32_bf16 v[72:75], v[88:91], v[10:13], v[72:75]
	v_mfma_f32_16x16x32_bf16 v[72:75], v[92:95], v[6:9], v[72:75]
	v_lshlrev_b32_e32 v39, 16, v39
	v_lshlrev_b32_e32 v40, 16, v40
	v_lshlrev_b32_e32 v41, 16, v41
	v_lshlrev_b32_e32 v42, 16, v42
	s_nop 7
	v_add_f32_e32 v76, v72, v39
	v_add_f32_e32 v77, v73, v40
	v_add_f32_e32 v78, v74, v41
	v_add_f32_e32 v79, v75, v42
	v_bfe_u32 v144, v76, 16, 1
	v_bfe_u32 v145, v77, 16, 1
	v_bfe_u32 v146, v78, 16, 1
	v_bfe_u32 v147, v79, 16, 1
	v_add3_u32 v76, v76, v144, s27
	v_add3_u32 v77, v77, v145, s27
	v_add3_u32 v78, v78, v146, s27
	v_add3_u32 v79, v79, v147, s27
	global_store_short_d16_hi v[62:63], v76, off offset:-4096
	global_store_short_d16_hi v[62:63], v77, off offset:-2048
	global_store_short_d16_hi v[62:63], v78, off
	global_store_short_d16_hi v[62:63], v79, off offset:2048
	s_waitcnt vmcnt(20)
	v_mfma_f32_16x16x32_bf16 v[72:75], v[96:99], v[18:21], 0
	v_mfma_f32_16x16x32_bf16 v[72:75], v[100:103], v[14:17], v[72:75]
	v_mfma_f32_16x16x32_bf16 v[72:75], v[104:107], v[10:13], v[72:75]
	v_mfma_f32_16x16x32_bf16 v[72:75], v[108:111], v[6:9], v[72:75]
	v_lshlrev_b32_e32 v43, 16, v43
	v_lshlrev_b32_e32 v44, 16, v44
	v_lshlrev_b32_e32 v45, 16, v45
	v_lshlrev_b32_e32 v46, 16, v46
	s_nop 7
	v_add_f32_e32 v76, v72, v43
	v_add_f32_e32 v77, v73, v44
	v_add_f32_e32 v78, v74, v45
	v_add_f32_e32 v79, v75, v46
	v_bfe_u32 v144, v76, 16, 1
	v_bfe_u32 v145, v77, 16, 1
	v_bfe_u32 v146, v78, 16, 1
	v_bfe_u32 v147, v79, 16, 1
	v_add3_u32 v76, v76, v144, s27
	v_add3_u32 v77, v77, v145, s27
	v_add3_u32 v78, v78, v146, s27
	v_add3_u32 v79, v79, v147, s27
	global_store_short_d16_hi v[64:65], v76, off offset:-4096
	global_store_short_d16_hi v[64:65], v77, off offset:-2048
	global_store_short_d16_hi v[64:65], v78, off
	global_store_short_d16_hi v[64:65], v79, off offset:2048
	s_waitcnt vmcnt(16)
	v_mfma_f32_16x16x32_bf16 v[72:75], v[112:115], v[18:21], 0
	v_mfma_f32_16x16x32_bf16 v[72:75], v[116:119], v[14:17], v[72:75]
	v_mfma_f32_16x16x32_bf16 v[72:75], v[120:123], v[10:13], v[72:75]
	v_mfma_f32_16x16x32_bf16 v[72:75], v[124:127], v[6:9], v[72:75]
	v_lshlrev_b32_e32 v47, 16, v47
	v_lshlrev_b32_e32 v48, 16, v48
	v_lshlrev_b32_e32 v49, 16, v49
	v_lshlrev_b32_e32 v50, 16, v50
	s_nop 7
	v_add_f32_e32 v76, v72, v47
	v_add_f32_e32 v77, v73, v48
	v_add_f32_e32 v78, v74, v49
	v_add_f32_e32 v79, v75, v50
	v_bfe_u32 v144, v76, 16, 1
	v_bfe_u32 v145, v77, 16, 1
	v_bfe_u32 v146, v78, 16, 1
	v_bfe_u32 v147, v79, 16, 1
	v_add3_u32 v76, v76, v144, s27
	v_add3_u32 v77, v77, v145, s27
	v_add3_u32 v78, v78, v146, s27
	v_add3_u32 v79, v79, v147, s27
	global_store_short_d16_hi v[66:67], v76, off offset:-4096
	global_store_short_d16_hi v[66:67], v77, off offset:-2048
	global_store_short_d16_hi v[66:67], v78, off
	global_store_short_d16_hi v[66:67], v79, off offset:2048
	s_waitcnt vmcnt(12)
	v_mfma_f32_16x16x32_bf16 v[72:75], v[128:131], v[18:21], 0
	v_mfma_f32_16x16x32_bf16 v[72:75], v[132:135], v[14:17], v[72:75]
	v_mfma_f32_16x16x32_bf16 v[72:75], v[136:139], v[10:13], v[72:75]
	v_mfma_f32_16x16x32_bf16 v[72:75], v[140:143], v[6:9], v[72:75]
	v_lshlrev_b32_e32 v51, 16, v51
	v_lshlrev_b32_e32 v52, 16, v52
	v_lshlrev_b32_e32 v53, 16, v53
	v_lshlrev_b32_e32 v54, 16, v54
	s_nop 7
	v_add_f32_e32 v76, v72, v51
	v_add_f32_e32 v77, v73, v52
	v_add_f32_e32 v78, v74, v53
	v_add_f32_e32 v79, v75, v54
	v_bfe_u32 v144, v76, 16, 1
	v_bfe_u32 v145, v77, 16, 1
	v_bfe_u32 v146, v78, 16, 1
	v_bfe_u32 v147, v79, 16, 1
	v_add3_u32 v76, v76, v144, s27
	v_add3_u32 v77, v77, v145, s27
	v_add3_u32 v78, v78, v146, s27
	v_add3_u32 v79, v79, v147, s27
	global_store_short_d16_hi v[68:69], v76, off offset:-4096
	global_store_short_d16_hi v[68:69], v77, off offset:-2048
	global_store_short_d16_hi v[68:69], v78, off
	global_store_short_d16_hi v[68:69], v79, off offset:2048
	s_cmp_eq_u32 s8, 4
	s_waitcnt lgkmcnt(0)
	s_barrier
	s_cbranch_scc0 .LBB0_203
	s_add_i32 s50, s50, s52
	s_cmpk_gt_i32 s50, 0xff
	s_cbranch_scc0 .LBB0_202
